# baseline (speedup 1.0000x reference)
; __device__ __forceinline__ void hgrn_phase(const Params& P, char* shm, int lbid) {
;     ...
;         for (int vt = 0; vt < 8; ++vt) {
;           const bf16x8 bv = *(const bf16x8*)(pb + PB_VT + (vt * 16 + fr) * TSTR + quad * 16);
;           f32x4 t = __builtin_amdgcn_mfma_f32_16x16x32_bf16(a, bv, Sacc[vt], 0, 0, 0);
;           t[0] *= gl.x; t[1] *= gl.y; t[2] *= gl.z; t[3] *= gl.w;
;           Sacc[vt] = t;
;         }
;       }
;       {
;         const int tt = w >> 2, vt0 = (w & 3) * 2;
;         bf16x8 qf[4];
; #pragma unroll
;         for (int ks = 0; ks < 4; ++ks) qf[ks] = *(const bf16x8*)(pb + PB_Q + (tt * 16 + fr) * QSTR + (ks * 32 + quad * 8) * 2);
;         f32x4 AT[2];
; #pragma unroll
;         for (int st = 0; st < 2; ++st) {
;           f32x4 acc = f32x4{0.f, 0.f, 0.f, 0.f};
; #pragma unroll
;           for (int ks = 0; ks < 4; ++ks) {
;             const bf16x8 kf = *(const bf16x8*)(pb + PB_K + (st * 16 + fr) * QSTR + (ks * 32 + quad * 8) * 2);
;             acc = __builtin_amdgcn_mfma_f32_16x16x32_bf16(kf, qf[ks], acc, 0, 0, 0);
;           }
;           const int tpos = tt * 16 + fr;
; #pragma unroll
;           for (int jj = 0; jj < 4; ++jj)
;             if (st * 16 + quad * 4 + jj > tpos) acc[jj] = 0.0f;
;           AT[st] = acc;
;         }
;         u32x4 ap;
;         ap.x = pack2(AT[0][0], AT[0][1]); ap.y = pack2(AT[0][2], AT[0][3]);
;         ap.z = pack2(AT[1][0], AT[1][1]); ap.w = pack2(AT[1][2], AT[1][3]);
;         const int r0 = HG_R0(c);
; #pragma unroll
;         for (int e = 0; e < 2; ++e) {
;           const int vt = vt0 + e;
;           f32x4 O = f32x4{0.f, 0.f, 0.f, 0.f};
; #pragma unroll
;           for (int ks = 0; ks < 4; ++ks) {
;             const bf16x8 sf = *(const bf16x8*)(sb + (vt * 16 + fr) * QSTR + (ks * 32 + quad * 8) * 2);
;             O = __builtin_amdgcn_mfma_f32_16x16x32_bf16(qf[ks], sf, O, 0, 0, 0);
;           }
;           const char* vp = pb + PB_VT + (vt * 16 + fr) * TSTR + quad * 8;
;           const u32x2 lo = *(const u32x2*)vp, hi = *(const u32x2*)(vp + 32);
;           u32x4 bp; bp.x = lo.x; bp.y = lo.y; bp.z = hi.x; bp.w = hi.y;
;           O = __builtin_amdgcn_mfma_f32_16x16x32_bf16(__builtin_bit_cast(bf16x8, ap), __builtin_bit_cast(bf16x8, bp), O, 0, 0, 0);
; #pragma unroll
;           for (int jj = 0; jj < 4; ++jj)
.LBB0_926:
	s_waitcnt lgkmcnt(0)
	v_add3_u32 v204, s74, v69, v90
	ds_read_b128 v[168:171], v75
	ds_read_b128 v[172:175], v75 offset:64
	ds_read_b128 v[176:179], v75 offset:128
	ds_read_b128 v[180:183], v75 offset:192
	v_add_u32_e32 v205, 0x6800, v204
	ds_read2_b64 v[200:203], v205 offset0:128 offset1:132
	ds_read_b128 v[184:187], v75 offset:4352
	ds_read_b128 v[188:191], v75 offset:4416
	ds_read_b128 v[192:195], v75 offset:4480
	ds_read_b128 v[196:199], v75 offset:4544
	v_add_u32_e32 v204, 0x7000, v204
	ds_read2_b64 v[130:133], v204 offset0:32 offset1:36
	v_pk_mul_f32 v[24:25], v[64:65], v[8:9]
	v_pk_mul_f32 v[8:9], v[64:65], v[56:57]
	v_mov_b32_e32 v56, s75
	v_cndmask_b32_e64 v56, v52, v56, s[16:17]
	v_cndmask_b32_e64 v56, v56, v52, s[14:15]
	v_mov_b32_e32 v52, s75
	v_pk_mul_f32 v[26:27], v[66:67], v[10:11]
	v_pk_mul_f32 v[10:11], v[66:67], v[58:59]
	v_cndmask_b32_e64 v53, 0, v53, s[14:15]
	v_cndmask_b32_e64 v54, v54, 0, s[18:19]
	v_cndmask_b32_e64 v55, v55, 0, s[20:21]
	v_cndmask_b32_e64 v57, v60, v52, s[6:7]
	v_cndmask_b32_e64 v58, v61, 0, s[8:9]
	v_cndmask_b32_e64 v59, v62, 0, s[10:11]
	v_cndmask_b32_e64 v60, v63, 0, s[12:13]
	v_cvt_pk_bf16_f32 v52, v56, v53
	v_cvt_pk_bf16_f32 v53, v54, v55
	v_cvt_pk_bf16_f32 v54, v57, v58
	v_cvt_pk_bf16_f32 v55, v59, v60
	s_waitcnt lgkmcnt(9)
	v_mfma_f32_16x16x32_bf16 v[56:59], v[48:51], v[168:171], 0
	v_add3_u32 v127, s74, v69, v90
	s_waitcnt lgkmcnt(8)
	v_mfma_f32_16x16x32_bf16 v[56:59], v[44:47], v[172:175], v[56:59]
	v_pk_mul_f32 v[4:5], v[64:65], v[4:5]
	v_pk_mul_f32 v[12:13], v[64:65], v[12:13]
	s_waitcnt lgkmcnt(7)
	v_mfma_f32_16x16x32_bf16 v[56:59], v[40:43], v[176:179], v[56:59]
	v_pk_mul_f32 v[16:17], v[64:65], v[16:17]
	v_pk_mul_f32 v[20:21], v[64:65], v[20:21]
	s_waitcnt lgkmcnt(6)
	v_mfma_f32_16x16x32_bf16 v[56:59], v[36:39], v[180:183], v[56:59]
	v_pk_mul_f32 v[28:29], v[64:65], v[28:29]
	s_waitcnt lgkmcnt(5)
	v_mfma_f32_16x16x32_bf16 v[56:59], v[52:55], v[200:203], v[56:59]
	v_add_u32_e32 v60, s5, v89
	v_ashrrev_i32_e32 v61, 31, v60
	v_add_u32_e32 v62, s5, v88
	v_lshlrev_b64 v[60:61], 11, v[60:61]
	v_ashrrev_i32_e32 v63, 31, v62
	v_lshl_add_u64 v[60:61], v[70:71], 0, v[60:61]
	v_lshlrev_b64 v[62:63], 11, v[62:63]
	s_nop 0
	global_store_dword v[60:61], v56, off
	v_lshl_add_u64 v[62:63], v[70:71], 0, v[62:63]
	v_add_u32_e32 v56, s5, v87
	global_store_dword v[62:63], v57, off
	v_ashrrev_i32_e32 v57, 31, v56
	v_lshlrev_b64 v[56:57], 11, v[56:57]
	v_pk_mul_f32 v[32:33], v[64:65], v[32:33]
	v_lshl_add_u64 v[64:65], v[70:71], 0, v[56:57]
	v_add_u32_e32 v56, s5, v86
	v_ashrrev_i32_e32 v57, 31, v56
	v_lshlrev_b64 v[56:57], 11, v[56:57]
	v_pk_mul_f32 v[6:7], v[66:67], v[6:7]
	v_pk_mul_f32 v[14:15], v[66:67], v[14:15]
	v_pk_mul_f32 v[18:19], v[66:67], v[18:19]
	v_pk_mul_f32 v[22:23], v[66:67], v[22:23]
	v_pk_mul_f32 v[30:31], v[66:67], v[30:31]
	v_pk_mul_f32 v[34:35], v[66:67], v[34:35]
	v_lshl_add_u64 v[66:67], v[70:71], 0, v[56:57]
	global_store_dword v[64:65], v58, off
	global_store_dword v[66:67], v59, off
	s_waitcnt lgkmcnt(4)
	v_mfma_f32_16x16x32_bf16 v[48:51], v[48:51], v[184:187], 0
	s_add_i32 s50, s50, 32
	s_sub_i32 s51, s51, 32
	s_waitcnt lgkmcnt(3)
	v_mfma_f32_16x16x32_bf16 v[44:47], v[44:47], v[188:191], v[48:51]
	s_nop 1
	s_waitcnt lgkmcnt(2)
	v_mfma_f32_16x16x32_bf16 v[40:43], v[40:43], v[192:195], v[44:47]
	s_nop 2
	s_cmpk_eq_i32 s50, 0x8c0
	s_waitcnt lgkmcnt(1)
	v_mfma_f32_16x16x32_bf16 v[36:39], v[36:39], v[196:199], v[40:43]
	s_nop 2
	s_waitcnt lgkmcnt(0)
	v_mfma_f32_16x16x32_bf16 v[36:39], v[52:55], v[130:133], v[36:39]
	s_nop 7
	global_store_dword v[60:61], v36, off offset:64
	global_store_dword v[62:63], v37, off offset:64
	global_store_dword v[64:65], v38, off offset:64
	global_store_dword v[66:67], v39, off offset:64
	s_barrier
	s_waitcnt vmcnt(9)
	v_mov_b32_e32 v125, v206
	v_mov_b32_e32 v124, v207
	v_mov_b32_e32 v123, v208
	v_mov_b32_e32 v121, v209
	v_mov_b32_e32 v120, v211
	v_mov_b32_e32 v119, v212
	v_mov_b32_e32 v122, v210
	v_mov_b32_e32 v118, v213
	s_cbranch_scc1 .LBB0_928
	s_mov_b32 s61, s4
	v_mov_b64_e32 v[36:37], v[4:5]
	v_mov_b64_e32 v[38:39], v[6:7]
	v_mov_b64_e32 v[40:41], v[12:13]
	v_mov_b64_e32 v[42:43], v[14:15]
	v_mov_b64_e32 v[44:45], v[16:17]
	v_mov_b64_e32 v[46:47], v[18:19]
	v_mov_b64_e32 v[48:49], v[20:21]
	v_mov_b64_e32 v[50:51], v[22:23]
	v_mov_b64_e32 v[52:53], v[24:25]
	v_mov_b64_e32 v[54:55], v[26:27]
	v_mov_b64_e32 v[56:57], v[28:29]
	v_mov_b64_e32 v[58:59], v[30:31]
	v_mov_b64_e32 v[60:61], v[32:33]
	v_mov_b64_e32 v[62:63], v[34:35]
	v_mov_b64_e32 v[64:65], v[8:9]
	v_mov_b64_e32 v[66:67], v[10:11]
	s_branch .LBB0_908
